# P2 hg_state gate pass 2: all 16 K-word LDS reads issued as one batch, gate steps software-pipelined (no per-step LDS round trip)
# speedup vs baseline: 1.0118x; 1.0049x over previous
.LBB0_284:
	s_or_b64 exec, exec, s[14:15]
	v_mul_u32_u24_e32 v43, 0x110, v43
	v_add_u32_e32 v43, v93, v43
	ds_read_b32 v220, v43
	v_mul_u32_u24_e32 v42, 0x110, v42
	v_add_u32_e32 v42, v93, v42
	ds_read_b32 v221, v42
	v_mul_u32_u24_e32 v41, 0x110, v41
	v_add_u32_e32 v41, v93, v41
	ds_read_b32 v222, v41
	v_mul_u32_u24_e32 v40, 0x110, v40
	v_add_u32_e32 v40, v93, v40
	ds_read_b32 v223, v40
	v_mul_u32_u24_e32 v38, 0x110, v38
	v_add_u32_e32 v38, v93, v38
	ds_read_b32 v224, v38
	v_mul_u32_u24_e32 v39, 0x110, v39
	v_add_u32_e32 v39, v93, v39
	ds_read_b32 v225, v39
	v_mul_u32_u24_e32 v37, 0x110, v37
	v_add_u32_e32 v37, v93, v37
	ds_read_b32 v226, v37
	v_mul_u32_u24_e32 v35, 0x110, v35
	v_add_u32_e32 v35, v93, v35
	ds_read_b32 v227, v35
	v_mul_u32_u24_e32 v36, 0x110, v36
	v_add_u32_e32 v36, v93, v36
	ds_read_b32 v228, v36
	v_mul_u32_u24_e32 v34, 0x110, v34
	v_add_u32_e32 v34, v93, v34
	ds_read_b32 v229, v34
	v_mul_u32_u24_e32 v33, 0x110, v33
	v_add_u32_e32 v33, v93, v33
	ds_read_b32 v230, v33
	v_mul_u32_u24_e32 v32, 0x110, v32
	v_add_u32_e32 v32, v93, v32
	ds_read_b32 v231, v32
	v_mul_u32_u24_e32 v31, 0x110, v31
	v_add_u32_e32 v31, v93, v31
	ds_read_b32 v232, v31
	v_mul_u32_u24_e32 v30, 0x110, v30
	v_add_u32_e32 v30, v93, v30
	ds_read_b32 v233, v30
	v_mul_u32_u24_e32 v29, 0x110, v29
	v_add_u32_e32 v29, v93, v29
	ds_read_b32 v234, v29
	v_mul_u32_u24_e32 v28, 0x110, v28
	v_add_u32_e32 v28, v93, v28
	ds_read_b32 v235, v28
	s_waitcnt lgkmcnt(15)
	v_lshlrev_b32_e32 v44, 16, v220
	v_and_b32_e32 v45, 0xffff0000, v220
	v_sub_f32_e32 v46, 1.0, v44
	v_sub_f32_e32 v47, 1.0, v45
	v_mul_f32_e32 v26, v26, v46
	v_mul_f32_e32 v27, v27, v47
	v_max_f32_e32 v46, 0xda24260, v26
	v_max_f32_e32 v47, 0xda24260, v27
	v_rcp_f32_e32 v46, v46
	v_rcp_f32_e32 v47, v47
	v_mov_b64_e32 v[86:87], s[12:13]
	s_waitcnt lgkmcnt(14)
	v_lshlrev_b32_e32 v244, 16, v221
	v_and_b32_e32 v245, 0xffff0000, v221
	v_sub_f32_e32 v242, 1.0, v244
	v_sub_f32_e32 v243, 1.0, v245
	v_pk_mul_f32 v[44:45], v[46:47], v[44:45]
	v_mul_f32_e32 v26, v26, v242
	v_mul_f32_e32 v27, v27, v243
	v_max_f32_e32 v242, 0xda24260, v26
	v_max_f32_e32 v243, 0xda24260, v27
	v_rcp_f32_e32 v242, v242
	v_rcp_f32_e32 v243, v243
	v_cvt_pk_bf16_f32 v44, v44, v45
	ds_write_b32 v43, v44
	s_waitcnt lgkmcnt(14)
	v_lshlrev_b32_e32 v44, 16, v222
	v_and_b32_e32 v45, 0xffff0000, v222
	v_sub_f32_e32 v46, 1.0, v44
	v_sub_f32_e32 v47, 1.0, v45
	v_pk_mul_f32 v[244:245], v[242:243], v[244:245]
	v_mul_f32_e32 v26, v26, v46
	v_mul_f32_e32 v27, v27, v47
	v_max_f32_e32 v46, 0xda24260, v26
	v_max_f32_e32 v47, 0xda24260, v27
	v_rcp_f32_e32 v46, v46
	v_rcp_f32_e32 v47, v47
	v_cvt_pk_bf16_f32 v244, v244, v245
	ds_write_b32 v42, v244
	s_waitcnt lgkmcnt(14)
	v_lshlrev_b32_e32 v244, 16, v223
	v_and_b32_e32 v245, 0xffff0000, v223
	v_sub_f32_e32 v242, 1.0, v244
	v_sub_f32_e32 v243, 1.0, v245
	v_pk_mul_f32 v[44:45], v[46:47], v[44:45]
	v_mul_f32_e32 v26, v26, v242
	v_mul_f32_e32 v27, v27, v243
	v_max_f32_e32 v242, 0xda24260, v26
	v_max_f32_e32 v243, 0xda24260, v27
	v_rcp_f32_e32 v242, v242
	v_rcp_f32_e32 v243, v243
	v_cvt_pk_bf16_f32 v44, v44, v45
	ds_write_b32 v41, v44
	global_load_dwordx4 v[18:21], v238, s[100:101]
	s_waitcnt lgkmcnt(14)
	v_lshlrev_b32_e32 v44, 16, v224
	v_and_b32_e32 v45, 0xffff0000, v224
	v_sub_f32_e32 v46, 1.0, v44
	v_sub_f32_e32 v47, 1.0, v45
	v_pk_mul_f32 v[244:245], v[242:243], v[244:245]
	v_mul_f32_e32 v26, v26, v46
	v_mul_f32_e32 v27, v27, v47
	v_max_f32_e32 v46, 0xda24260, v26
	v_max_f32_e32 v47, 0xda24260, v27
	v_rcp_f32_e32 v46, v46
	v_rcp_f32_e32 v47, v47
	v_cvt_pk_bf16_f32 v244, v244, v245
	ds_write_b32 v40, v244
	s_waitcnt lgkmcnt(14)
	v_lshlrev_b32_e32 v244, 16, v225
	v_and_b32_e32 v245, 0xffff0000, v225
	v_sub_f32_e32 v242, 1.0, v244
	v_sub_f32_e32 v243, 1.0, v245
	v_pk_mul_f32 v[44:45], v[46:47], v[44:45]
	v_mul_f32_e32 v26, v26, v242
	v_mul_f32_e32 v27, v27, v243
	v_max_f32_e32 v242, 0xda24260, v26
	v_max_f32_e32 v243, 0xda24260, v27
	v_rcp_f32_e32 v242, v242
	v_rcp_f32_e32 v243, v243
	v_cvt_pk_bf16_f32 v44, v44, v45
	ds_write_b32 v38, v44
	s_waitcnt lgkmcnt(14)
	v_lshlrev_b32_e32 v44, 16, v226
	v_and_b32_e32 v45, 0xffff0000, v226
	v_sub_f32_e32 v46, 1.0, v44
	v_sub_f32_e32 v47, 1.0, v45
	v_pk_mul_f32 v[244:245], v[242:243], v[244:245]
	v_mul_f32_e32 v26, v26, v46
	v_mul_f32_e32 v27, v27, v47
	v_max_f32_e32 v46, 0xda24260, v26
	v_max_f32_e32 v47, 0xda24260, v27
	v_rcp_f32_e32 v46, v46
	v_rcp_f32_e32 v47, v47
	v_cvt_pk_bf16_f32 v244, v244, v245
	ds_write_b32 v39, v244
	global_load_dwordx4 v[6:9], v239, s[100:101]
	s_waitcnt lgkmcnt(14)
	v_lshlrev_b32_e32 v244, 16, v227
	v_and_b32_e32 v245, 0xffff0000, v227
	v_sub_f32_e32 v242, 1.0, v244
	v_sub_f32_e32 v243, 1.0, v245
	v_pk_mul_f32 v[44:45], v[46:47], v[44:45]
	v_mul_f32_e32 v26, v26, v242
	v_mul_f32_e32 v27, v27, v243
	v_max_f32_e32 v242, 0xda24260, v26
	v_max_f32_e32 v243, 0xda24260, v27
	v_rcp_f32_e32 v242, v242
	v_rcp_f32_e32 v243, v243
	v_cvt_pk_bf16_f32 v44, v44, v45
	ds_write_b32 v37, v44
	s_waitcnt lgkmcnt(14)
	v_lshlrev_b32_e32 v44, 16, v228
	v_and_b32_e32 v45, 0xffff0000, v228
	v_sub_f32_e32 v46, 1.0, v44
	v_sub_f32_e32 v47, 1.0, v45
	v_pk_mul_f32 v[244:245], v[242:243], v[244:245]
	v_mul_f32_e32 v26, v26, v46
	v_mul_f32_e32 v27, v27, v47
	v_max_f32_e32 v46, 0xda24260, v26
	v_max_f32_e32 v47, 0xda24260, v27
	v_rcp_f32_e32 v46, v46
	v_rcp_f32_e32 v47, v47
	v_cvt_pk_bf16_f32 v244, v244, v245
	ds_write_b32 v35, v244
	s_waitcnt lgkmcnt(14)
	v_lshlrev_b32_e32 v244, 16, v229
	v_and_b32_e32 v245, 0xffff0000, v229
	v_sub_f32_e32 v242, 1.0, v244
	v_sub_f32_e32 v243, 1.0, v245
	v_pk_mul_f32 v[44:45], v[46:47], v[44:45]
	v_mul_f32_e32 v26, v26, v242
	v_mul_f32_e32 v27, v27, v243
	v_max_f32_e32 v242, 0xda24260, v26
	v_max_f32_e32 v243, 0xda24260, v27
	v_rcp_f32_e32 v242, v242
	v_rcp_f32_e32 v243, v243
	v_cvt_pk_bf16_f32 v44, v44, v45
	ds_write_b32 v36, v44
	global_load_dwordx4 v[14:17], v240, s[100:101]
	s_waitcnt lgkmcnt(14)
	v_lshlrev_b32_e32 v44, 16, v230
	v_and_b32_e32 v45, 0xffff0000, v230
	v_sub_f32_e32 v46, 1.0, v44
	v_sub_f32_e32 v47, 1.0, v45
	v_pk_mul_f32 v[244:245], v[242:243], v[244:245]
	v_mul_f32_e32 v26, v26, v46
	v_mul_f32_e32 v27, v27, v47
	v_max_f32_e32 v46, 0xda24260, v26
	v_max_f32_e32 v47, 0xda24260, v27
	v_rcp_f32_e32 v46, v46
	v_rcp_f32_e32 v47, v47
	v_cvt_pk_bf16_f32 v244, v244, v245
	ds_write_b32 v34, v244
	s_waitcnt lgkmcnt(14)
	v_lshlrev_b32_e32 v244, 16, v231
	v_and_b32_e32 v245, 0xffff0000, v231
	v_sub_f32_e32 v242, 1.0, v244
	v_sub_f32_e32 v243, 1.0, v245
	v_pk_mul_f32 v[44:45], v[46:47], v[44:45]
	v_mul_f32_e32 v26, v26, v242
	v_mul_f32_e32 v27, v27, v243
	v_max_f32_e32 v242, 0xda24260, v26
	v_max_f32_e32 v243, 0xda24260, v27
	v_rcp_f32_e32 v242, v242
	v_rcp_f32_e32 v243, v243
	v_cvt_pk_bf16_f32 v44, v44, v45
	ds_write_b32 v33, v44
	s_waitcnt lgkmcnt(14)
	v_lshlrev_b32_e32 v44, 16, v232
	v_and_b32_e32 v45, 0xffff0000, v232
	v_sub_f32_e32 v46, 1.0, v44
	v_sub_f32_e32 v47, 1.0, v45
	v_pk_mul_f32 v[244:245], v[242:243], v[244:245]
	v_mul_f32_e32 v26, v26, v46
	v_mul_f32_e32 v27, v27, v47
	v_max_f32_e32 v46, 0xda24260, v26
	v_max_f32_e32 v47, 0xda24260, v27
	v_rcp_f32_e32 v46, v46
	v_rcp_f32_e32 v47, v47
	v_cvt_pk_bf16_f32 v244, v244, v245
	ds_write_b32 v32, v244
	global_load_dwordx4 v[22:25], v241, s[100:101]
	s_waitcnt lgkmcnt(14)
	v_lshlrev_b32_e32 v244, 16, v233
	v_and_b32_e32 v245, 0xffff0000, v233
	v_sub_f32_e32 v242, 1.0, v244
	v_sub_f32_e32 v243, 1.0, v245
	v_pk_mul_f32 v[44:45], v[46:47], v[44:45]
	v_mul_f32_e32 v26, v26, v242
	v_mul_f32_e32 v27, v27, v243
	v_max_f32_e32 v242, 0xda24260, v26
	v_max_f32_e32 v243, 0xda24260, v27
	v_rcp_f32_e32 v242, v242
	v_rcp_f32_e32 v243, v243
	v_cvt_pk_bf16_f32 v44, v44, v45
	ds_write_b32 v31, v44
	s_waitcnt lgkmcnt(14)
	v_lshlrev_b32_e32 v44, 16, v234
	v_and_b32_e32 v45, 0xffff0000, v234
	v_sub_f32_e32 v46, 1.0, v44
	v_sub_f32_e32 v47, 1.0, v45
	v_pk_mul_f32 v[244:245], v[242:243], v[244:245]
	v_mul_f32_e32 v26, v26, v46
	v_mul_f32_e32 v27, v27, v47
	v_max_f32_e32 v46, 0xda24260, v26
	v_max_f32_e32 v47, 0xda24260, v27
	v_rcp_f32_e32 v46, v46
	v_rcp_f32_e32 v47, v47
	v_cvt_pk_bf16_f32 v244, v244, v245
	ds_write_b32 v30, v244
	s_waitcnt lgkmcnt(14)
	v_lshlrev_b32_e32 v244, 16, v235
	v_and_b32_e32 v245, 0xffff0000, v235
	v_sub_f32_e32 v242, 1.0, v244
	v_sub_f32_e32 v243, 1.0, v245
	v_pk_mul_f32 v[44:45], v[46:47], v[44:45]
	v_mul_f32_e32 v26, v26, v242
	v_mul_f32_e32 v27, v27, v243
	v_max_f32_e32 v242, 0xda24260, v26
	v_max_f32_e32 v243, 0xda24260, v27
	v_rcp_f32_e32 v242, v242
	v_rcp_f32_e32 v243, v243
	v_cvt_pk_bf16_f32 v44, v44, v45
	ds_write_b32 v29, v44
	s_nop 0
	v_pk_mul_f32 v[244:245], v[242:243], v[244:245]
	s_nop 0
	v_cvt_pk_bf16_f32 v244, v244, v245
	ds_write_b32 v28, v244
	s_waitcnt lgkmcnt(0)
	s_barrier
	s_and_saveexec_b64 s[42:43], s[40:41]
	s_cbranch_execz .LBB0_273
	ds_read2st64_b32 v[26:27], v110 offset0:204 offset1:206
	ds_read2st64_b32 v[28:29], v110 offset0:208 offset1:210
	s_bfe_i64 s[14:15], s[12:13], 0x200000
	v_mov_b64_e32 v[86:87], s[14:15]
	s_waitcnt lgkmcnt(1)
	v_mov_b32_e32 v30, v26
	s_waitcnt lgkmcnt(0)
	v_mov_b32_e32 v31, v28
	v_mov_b32_e32 v28, v27
	v_pk_mul_f32 v[26:27], v[30:31], v[28:29]
	s_nop 0
	v_mul_f32_e32 v26, v26, v27
	global_store_dword v[84:85], v26, off
	s_branch .LBB0_273
